# chunk_prep: operand-fragment stores of a task issued by the next trip after its last load wait (not in a burst right before the next task's loads), on top of previous best
# speedup vs baseline: 1.0028x; 1.0011x over previous
; #define GAS __attribute__((address_space(1)))
; DI void chunk_prep(const bf16* PROJ, const float* mu, const bf16* LO, const float* pw0, const float* pa0, const float* pkk, const float* pka, const float* prk, float* SCAL, unsigned char* OPS, float* G15, LAS unsigned char* lds, int gw, int NGW, int wave, int lane) {
;     LAS unsigned char* base = lds + wave * 16384;
;     const int d = lane, x = lane & 15, q = lane >> 4;
;     for (int task = gw; task < NTASK; task += NGW) {
;         const int chain = task / NCHUNK, c = task - chain * NCHUNK, bb = chain >> 3, hd = chain & 7;
;         const size_t m0 = (size_t)bb * SEQ + (size_t)c * 16;
;         float a[16], b[16], k[16], r[16]; float g = 1.f;
;         {
;             const int ch = hd * 64 + d;
;             const float w0v = ((const GAS float*)pw0)[ch], a0v = ((const GAS float*)pa0)[ch], kkv = ((const GAS float*)pkk)[ch], kav = ((const GAS float*)pka)[ch], rkv = ((const GAS float*)prk)[ch];
;             const float mur = ((const GAS float*)mu)[ch], muk = ((const GAS float*)mu)[512 + ch];
;             float w[16], wl[16], al[16];
;             { const GAS bf16* pj = (const GAS bf16*)PROJ + m0 * INP + (INC - RWC) + ch;
;               float pr_ = 0.f, pk_ = 0.f; if (c != 0) { pr_ = bf2f(*(pj - INP)); pk_ = bf2f(*(pj - INP + 512)); }
; #pragma unroll
;               for (int t = 0; t < 16; ++t) { const float xr = bf2f(pj[(size_t)t * INP]), xk = bf2f(pj[(size_t)t * INP + 512]); r[t] = xr + (pr_ - xr) * mur; k[t] = xk + (pk_ - xk) * muk; pr_ = xr; pk_ = xk; } }
; #pragma unroll
;             for (int t = 0; t < 16; ++t) { const size_t o = (m0 + t) * 1536 + ch; wl[t] = bf2f(((const GAS bf16*)LO)[o]); al[t] = bf2f(((const GAS bf16*)LO)[o + 512]); }
;             float nn[16], bo[16], av[16];
; #pragma unroll
;             for (int t = 0; t < 16; ++t) {
;                 const float z = -(w0v + wl[t]);
;                 w[t] = __builtin_amdgcn_exp2f(-1.4426950408889634f * 0.6065306597126334f * __builtin_amdgcn_rcpf(1.f + __builtin_amdgcn_exp2f(1.4426950408889634f * z)));
;                 av[t] = __builtin_amdgcn_rcpf(1.f + __builtin_amdgcn_exp2f(-1.4426950408889634f * (a0v + al[t])));
;                 const float kx = k[t] * kkv; a[t] = kx; nn[t] = kx * kx;
;                 const float kp = k[t] * (1.f + (av[t] - 1.f) * kav); k[t] = kp; bo[t] = r[t] * kp * rkv;
;             }
; #pragma unroll
.LBB0_853:
	s_mov_b32 s100, 0
	v_readlane_b32 s0, v254, 11
	s_mov_b64 s[10:11], s[96:97]
	s_mov_b64 s[2:3], s[96:97]
	s_waitcnt lgkmcnt(0)
	s_mov_b64 s[6:7], s[96:97]
	s_mov_b64 s[4:5], s[96:97]
	s_mov_b64 s[8:9], s[96:97]
	s_mov_b64 s[12:13], s[96:97]
	s_cmpk_gt_i32 s0, 0x3fff
	v_readlane_b32 s1, v254, 12
	s_cbranch_scc1 .LBB0_890
	s_add_u32 s20, s44, 0x52400000
	s_addc_u32 s21, s45, 0
	s_waitcnt vmcnt(0)
	v_and_b32_e32 v2, 15, v0
	v_lshrrev_b32_e32 v3, 2, v186
	v_readlane_b32 s16, v254, 11
	s_add_u32 s0, s44, 0x77600000
	v_and_b32_e32 v1, 48, v0
	v_and_b32_e32 v6, 12, v3
	v_lshlrev_b32_e32 v7, 6, v2
	v_lshlrev_b32_e32 v8, 5, v2
	v_readlane_b32 s17, v254, 12
	s_mov_b32 s50, s16
	s_load_dwordx2 s[18:19], s[10:11], 0x90
	s_load_dwordx2 s[22:23], s[2:3], 0x98
	s_load_dwordx2 s[24:25], s[6:7], 0xa8
	s_load_dwordx2 s[26:27], s[4:5], 0xc0
	s_load_dwordx2 s[28:29], s[8:9], 0xc8
	s_load_dwordx2 s[30:31], s[12:13], 0xd0
	s_addc_u32 s1, s45, 0
	v_or_b32_e32 v10, v7, v1
	v_or_b32_e32 v7, v6, v7
	v_lshl_or_b32 v12, v6, 1, v8
	v_cmp_lt_u32_e64 s[4:5], v6, v2
	v_cmp_gt_u32_e64 s[6:7], v6, v2
	v_or_b32_e32 v8, 1, v6
	v_or_b32_e32 v6, 2, v6
	s_ashr_i32 s51, s16, 31
	s_mul_hi_i32 s16, s16, 0x2800
	s_mul_i32 s17, s50, 0x2800
	v_cmp_lt_u32_e64 s[8:9], v6, v2
	v_cmp_gt_u32_e64 s[10:11], v6, v2
	v_lshlrev_b32_e32 v13, 1, v7
	v_lshl_or_b32 v6, v186, 4, s17
	v_mov_b32_e32 v7, s16
	v_readlane_b32 s16, v254, 7
	v_readlane_b32 s17, v254, 8
	v_or_b32_e32 v3, 3, v3
	s_mov_b32 s40, s16
	s_ashr_i32 s41, s16, 31
	s_mul_hi_i32 s35, s16, 0x2800
	s_mul_i32 s34, s16, 0x2800
	s_lshl_b64 s[16:17], s[50:51], 8
	v_lshl_or_b32 v5, v2, 7, v1
	v_lshlrev_b32_e32 v11, 2, v2
	v_cmp_lt_u32_e32 vcc, v8, v2
	v_cmp_lt_u32_e64 s[12:13], v3, v2
	v_cmp_gt_u32_e64 s[14:15], v3, v2
	v_lshl_or_b32 v2, v186, 2, s16
	v_mov_b32_e32 v3, s17
	s_mov_b64 s[16:17], 0x91100000
	v_readlane_b32 s2, v254, 9
	v_lshl_add_u64 v[8:9], v[2:3], 0, s[16:17]
	s_mov_b32 s16, s40
	v_readlane_b32 s3, v254, 10
	s_lshl_b32 s2, s2, 14
	v_writelane_b32 v254, s16, 7
	s_add_i32 s53, s2, 0
	v_lshlrev_b32_e32 v4, 5, v186
	v_writelane_b32 v254, s17, 8
	s_mov_b32 s43, 1.0
	s_mov_b32 s42, s50
	s_mov_b32 s52, 0
	v_cmp_eq_u32_e64 s[2:3], 0, v186
	v_lshl_add_u32 v1, v186, 1, s53
	s_lshl_b64 s[36:37], s[40:41], 8
	s_lshl_b64 s[38:39], s[50:51], 4
	s_lshl_b64 s[40:41], s[40:41], 4
	v_mov_b32_e32 v3, 0
	v_mov_b32_e32 v52, 0xc00
	s_mov_b64 s[48:49], 0xc00
	v_add_u32_e32 v53, s53, v4
	v_add_u32_e32 v54, s53, v5
	v_add_u32_e32 v55, s53, v10
	v_add_u32_e32 v56, s53, v11
	v_add_u32_e32 v57, s53, v13
	v_add_u32_e32 v58, s53, v12
	v_mov_b32_e32 v11, 1.0
	s_or_b64 s[16:17], s[8:9], vcc
	v_writelane_b32 v254, s42, 11
	s_mov_b32 s54, s50
	s_nop 0
	v_writelane_b32 v254, s43, 12
	s_branch .LBB0_856
.LBB0_855:
	s_or_b64 exec, exec, s[56:57]
	v_mov_b32_e32 v87, s89
	v_add_f32_e32 v87, s88, v87
	v_max_f32_e32 v87, 0x179abe15, v87
	v_rsq_f32_e32 v87, v87
	v_mov_b32_e32 v98, s86
	v_add_f32_e32 v98, s85, v98
	v_mov_b32_e32 v88, s90
	v_mul_f32_e32 v87, v90, v87
	v_max_f32_e32 v90, 0x179abe15, v98
	v_rsq_f32_e32 v90, v90
	v_mov_b32_e32 v98, s84
	v_add_f32_e32 v98, s83, v98
	v_max_f32_e32 v98, 0x179abe15, v98
	v_rsq_f32_e32 v99, v98
	v_add_f32_e32 v98, s87, v88
	v_mul_f32_e32 v88, v47, v90
	v_mov_b32_e32 v47, s80
	v_add_f32_e32 v47, s79, v47
	v_max_f32_e32 v47, 0x179abe15, v47
	v_rsq_f32_e32 v47, v47
	v_lshlrev_b32_e32 v74, 16, v74
	v_add_f32_e32 v74, v59, v74
	v_mul_f32_e32 v90, v46, v99
	v_mul_f32_e32 v47, v96, v47
	v_mov_b32_e32 v96, s78
	v_add_f32_e32 v96, s77, v96
	v_max_f32_e32 v96, 0x179abe15, v96
	v_rsq_f32_e32 v96, v96
	v_mov_b32_e32 v46, s82
	v_mul_f32_e32 v74, 0xbfb8aa3b, v74
	v_add_f32_e32 v46, s81, v46
	v_mul_f32_e32 v45, v45, v96
	v_mov_b32_e32 v96, s74
	v_add_f32_e32 v96, s73, v96
	v_max_f32_e32 v96, 0x179abe15, v96
	v_rsq_f32_e32 v96, v96
	v_exp_f32_e32 v74, v74
	v_max_f32_e32 v46, 0x179abe15, v46
	v_rsq_f32_e32 v46, v46
	v_mul_f32_e32 v95, v95, v96
	v_mov_b32_e32 v96, s68
	v_add_f32_e32 v96, s67, v96
	v_max_f32_e32 v96, 0x179abe15, v96
	v_rsq_f32_e32 v96, v96
	v_lshlrev_b32_e32 v83, 16, v83
	v_add_f32_e32 v74, 1.0, v74
	v_add_f32_e32 v83, v59, v83
	v_mul_f32_e32 v93, v93, v96
	v_mov_b32_e32 v96, s63
	v_add_f32_e32 v96, s62, v96
	v_max_f32_e32 v96, 0x179abe15, v96
	v_rsq_f32_e32 v96, v96
	v_rcp_f32_e32 v74, v74
	v_mul_f32_e32 v83, 0xbfb8aa3b, v83
	v_mul_f32_e32 v46, v97, v46
	v_mul_f32_e32 v91, v91, v96
	v_mov_b32_e32 v96, s59
	v_add_f32_e32 v96, s58, v96
	v_max_f32_e32 v96, 0x179abe15, v96
	v_mov_b32_e32 v97, s76
	v_rsq_f32_e32 v96, v96
	v_exp_f32_e32 v83, v83
	v_add_f32_e32 v97, s75, v97
	v_max_f32_e32 v97, 0x179abe15, v97
	v_rsq_f32_e32 v97, v97
	v_lshlrev_b32_e32 v82, 16, v82
	v_mul_f32_e32 v74, 0xbf60028a, v74
	v_mul_f32_e32 v49, v49, v96
	v_lshlrev_b32_e32 v80, 16, v80
	v_exp_f32_e32 v96, v74
	v_add_f32_e32 v74, 1.0, v83
	v_add_f32_e32 v82, v59, v82
	v_lshlrev_b32_e32 v79, 16, v79
	v_rcp_f32_e32 v74, v74
	v_mul_f32_e32 v82, 0xbfb8aa3b, v82
	v_add_f32_e32 v80, v59, v80
	v_exp_f32_e32 v82, v82
	v_mul_f32_e32 v80, 0xbfb8aa3b, v80
	v_add_f32_e32 v79, v59, v79
	v_mul_f32_e32 v44, v44, v97
	v_mov_b32_e32 v97, s70
	v_exp_f32_e32 v80, v80
	v_mul_f32_e32 v79, 0xbfb8aa3b, v79
	v_add_f32_e32 v97, s69, v97
	v_exp_f32_e32 v79, v79
	v_max_f32_e32 v97, 0x179abe15, v97
	v_mul_f32_e32 v74, 0xbf60028a, v74
	v_rsq_f32_e32 v97, v97
	v_exp_f32_e32 v83, v74
	v_add_f32_e32 v74, 1.0, v82
	v_rcp_f32_e32 v74, v74
	v_add_f32_e32 v80, 1.0, v80
	v_rcp_f32_e32 v80, v80
	v_add_f32_e32 v79, 1.0, v79
	v_rcp_f32_e32 v79, v79
	v_mul_f32_e32 v94, v94, v97
	v_mov_b32_e32 v97, s66
	v_add_f32_e32 v97, s65, v97
	v_mul_f32_e32 v74, 0xbf60028a, v74
	v_max_f32_e32 v97, 0x179abe15, v97
	s_waitcnt vmcnt(4)
; DI void chunk_prep(const bf16* PROJ, const float* mu, const bf16* LO, const float* pw0, const float* pa0, const float* pkk, const float* pka, const float* prk, float* SCAL, unsigned char* OPS, float* G15, LAS unsigned char* lds, int gw, int NGW, int wave, int lane) {
;     ...
;             for (int t = 0; t < 16; ++t) {
;                 const float z = -(w0v + wl[t]);
;                 w[t] = __builtin_amdgcn_exp2f(-1.4426950408889634f * 0.6065306597126334f * __builtin_amdgcn_rcpf(1.f + __builtin_amdgcn_exp2f(1.4426950408889634f * z)));
;                 av[t] = __builtin_amdgcn_rcpf(1.f + __builtin_amdgcn_exp2f(-1.4426950408889634f * (a0v + al[t])));
;                 const float kx = k[t] * kkv; a[t] = kx; nn[t] = kx * kx;
;                 const float kp = k[t] * (1.f + (av[t] - 1.f) * kav); k[t] = kp; bo[t] = r[t] * kp * rkv;
;             }
; #pragma unroll
;             for (int t = 0; t < 16; ++t) { { auto rr = __builtin_amdgcn_permlane32_swap(__float_as_uint(nn[t]), __float_as_uint(nn[t]), false, false); nn[t] = __uint_as_float(rr[0]) + __uint_as_float(rr[1]); }
;                                            { auto rr = __builtin_amdgcn_permlane32_swap(__float_as_uint(bo[t]), __float_as_uint(bo[t]), false, false); bo[t] = __uint_as_float(rr[0]) + __uint_as_float(rr[1]); } }
;     ...
;             CP_DPP_STEP(0x128) CP_DPP_STEP(0x124) CP_DPP_STEP(0x122) CP_DPP_STEP(0x121)
;     ...
; #pragma unroll
;             for (int t = 0; t < 16; ++t) {
;                 const float nsum = __builtin_bit_cast(float, __builtin_amdgcn_readlane(__builtin_bit_cast(int, nn[t]), 0)) + __builtin_bit_cast(float, __builtin_amdgcn_readlane(__builtin_bit_cast(int, nn[t]), 16));
;                 const float bon = __builtin_bit_cast(float, __builtin_amdgcn_readlane(__builtin_bit_cast(int, bo[t]), 0)) + __builtin_bit_cast(float, __builtin_amdgcn_readlane(__builtin_bit_cast(int, bo[t]), 16));
;                 if (lane == 0) ((GAS float*)SCAL)[((m0 + t) * 8 + hd) * 4 + 2] = bon;
;                 const float kn = a[t] * __builtin_amdgcn_rsqf(fmaxf(nsum, 1e-24f));
;                 a[t] = -kn; b[t] = kn * av[t];
;             }
; #pragma unroll
;             for (int t = 0; t < 16; ++t) { const float gm1 = g; g *= w[t]; const float inv = __builtin_amdgcn_rcpf(g); a[t] *= gm1; r[t] *= g; b[t] *= inv; k[t] *= inv; }
;     ...
;         unsigned char* ob = OPS + (size_t)task * OPS_TASK + lane * 16;
; #pragma unroll
	v_lshlrev_b32_e32 v84, 16, v84
	v_lshlrev_b32_e32 v85, 16, v85
	v_exp_f32_e32 v82, v74
	v_mul_f32_e32 v74, 0xbf60028a, v80
	v_rsq_f32_e32 v97, v97
	v_exp_f32_e32 v80, v74
	v_mul_f32_e32 v74, 0xbf60028a, v79
	v_add_f32_e32 v79, v59, v84
	v_add_f32_e32 v84, v59, v85
	v_mul_f32_e32 v79, 0xbfb8aa3b, v79
	v_mul_f32_e32 v84, 0xbfb8aa3b, v84
	v_exp_f32_e32 v79, v79
	v_exp_f32_e32 v84, v84
	v_mul_f32_e32 v92, v92, v97
	v_mov_b32_e32 v97, s61
	v_add_f32_e32 v97, s60, v97
	s_waitcnt vmcnt(2)
	v_lshlrev_b32_e32 v86, 16, v86
	v_max_f32_e32 v97, 0x179abe15, v97
	v_exp_f32_e32 v85, v74
	v_add_f32_e32 v74, 1.0, v79
	v_add_f32_e32 v79, 1.0, v84
	v_add_f32_e32 v84, v59, v86
	v_rsq_f32_e32 v97, v97
	v_rcp_f32_e32 v74, v74
	v_mul_f32_e32 v84, 0xbfb8aa3b, v84
	v_rcp_f32_e32 v79, v79
	v_exp_f32_e32 v84, v84
	v_mul_f32_e32 v89, v89, v97
	v_mov_b32_e32 v97, s55
	v_lshlrev_b32_e32 v76, 16, v76
	v_mul_f32_e32 v74, 0xbf60028a, v74
	v_add_f32_e32 v97, s42, v97
	v_exp_f32_e32 v86, v74
	v_mul_f32_e32 v74, 0xbf60028a, v79
	v_add_f32_e32 v79, 1.0, v84
	v_add_f32_e32 v76, v59, v76
	v_max_f32_e32 v97, 0x179abe15, v97
	v_rcp_f32_e32 v79, v79
	v_mul_f32_e32 v76, 0xbfb8aa3b, v76
	v_rsq_f32_e32 v97, v97
	v_exp_f32_e32 v76, v76
	v_lshlrev_b32_e32 v81, 16, v81
	v_lshlrev_b32_e32 v73, 16, v73
	v_add_f32_e32 v81, v59, v81
	s_waitcnt vmcnt(0)
	s_cmp_eq_u32 s100, 0
	s_cbranch_scc1 .Lmy_cps_skip_loop
	s_mov_b32 s98, 0x87101000
	s_mov_b32 s99, 0
	v_lshl_add_u64 v[240:241], s[44:45], 0, v[250:251]
	v_add_u32_e32 v244, 0x800, v57
	ds_read2_b64 v[200:203], v57 offset1:4
	ds_read2_b64 v[204:207], v244 offset1:4
	ds_read2_b64 v[208:211], v57 offset0:8 offset1:12
	ds_read2_b64 v[212:215], v244 offset0:8 offset1:12
	ds_read_b128 v[216:219], v55 offset:13312
	ds_read_b128 v[220:223], v55 offset:14336
	ds_read_b128 v[224:227], v55 offset:15360
	ds_read2st64_b64 v[228:231], v58 offset0:16 offset1:20
	ds_read2st64_b64 v[232:235], v58 offset0:17 offset1:21
	ds_read2st64_b64 v[236:239], v58 offset0:18 offset1:22
	ds_read2st64_b64 v[246:249], v58 offset0:19 offset1:23
	v_lshl_add_u64 v[240:241], v[240:241], 0, s[98:99]
	s_movk_i32 s98, 0x1000
	v_mov_b32_e32 v192, 0
	v_mov_b32_e32 v193, 0
	v_lshl_add_u64 v[242:243], v[240:241], 0, s[98:99]
	s_waitcnt lgkmcnt(0)
	v_cvt_pk_bf16_f32 v194, v216, v217
	v_cvt_pk_bf16_f32 v195, v218, v219
	v_cvt_pk_bf16_f32 v196, v220, v221
	v_cvt_pk_bf16_f32 v197, v222, v223
	v_cvt_pk_bf16_f32 v198, v224, v225
	v_cvt_pk_bf16_f32 v199, v226, v227
	global_store_dwordx4 v[240:241], v[200:203], off offset:-4096
	global_store_dwordx4 v[240:241], v[208:211], off offset:-3072
	global_store_dwordx4 v[240:241], v[192:195], off offset:-2048
	global_store_dwordx4 v[240:241], v[204:207], off offset:-1024
	global_store_dwordx4 v[240:241], v[212:215], off
	global_store_dwordx4 v[240:241], v[196:199], off offset:1024
	global_store_dwordx4 v[240:241], v[228:231], off offset:2048
	global_store_dwordx4 v[240:241], v[232:235], off offset:3072
	global_store_dwordx4 v[242:243], v[236:239], off
	global_store_dwordx4 v[242:243], v[246:249], off offset:1024
.Lmy_cps_skip_loop:
	v_lshlrev_b32_e32 v77, 16, v77
	v_exp_f32_e32 v84, v74
	v_mul_f32_e32 v74, 0xbf60028a, v79
	v_mul_f32_e32 v10, v10, v97
	v_mul_f32_e32 v81, 0xbfb8aa3b, v81
	v_lshlrev_b32_e32 v78, 16, v78
	v_add_f32_e32 v73, v59, v73
	v_exp_f32_e32 v97, v74
	v_add_f32_e32 v74, 1.0, v76
	v_add_f32_e32 v76, v59, v77
	v_exp_f32_e32 v81, v81
	v_mul_f32_e32 v73, 0xbfb8aa3b, v73
	v_mul_f32_e32 v76, 0xbfb8aa3b, v76
	v_add_f32_e32 v77, v59, v78
	v_lshlrev_b32_e32 v48, 16, v48
	v_exp_f32_e32 v73, v73
	v_exp_f32_e32 v76, v76
	v_mul_f32_e32 v77, 0xbfb8aa3b, v77
	v_exp_f32_e32 v77, v77
	v_add_f32_e32 v48, v59, v48
	v_mul_f32_e32 v48, 0xbfb8aa3b, v48
	v_add_f32_e32 v81, 1.0, v81
	v_exp_f32_e32 v48, v48
	v_rcp_f32_e32 v81, v81
	v_lshlrev_b32_e32 v75, 16, v75
	v_add_f32_e32 v73, 1.0, v73
	v_rcp_f32_e32 v74, v74
	v_add_f32_e32 v76, 1.0, v76
	v_rcp_f32_e32 v73, v73
	v_rcp_f32_e32 v76, v76
	v_add_f32_e32 v77, 1.0, v77
	v_add_f32_e32 v75, v59, v75
	v_rcp_f32_e32 v77, v77
	v_mul_f32_e32 v75, 0xbfb8aa3b, v75
	v_exp_f32_e32 v75, v75
	v_add_f32_e32 v48, 1.0, v48
	v_lshlrev_b32_e32 v43, 16, v43
	v_mul_f32_e32 v81, 0xbf60028a, v81
	v_mul_f32_e32 v74, 0xbf60028a, v74
	v_rcp_f32_e32 v48, v48
	v_exp_f32_e32 v81, v81
	v_mul_f32_e32 v73, 0xbf60028a, v73
	v_exp_f32_e32 v99, v74
	v_mul_f32_e32 v74, 0xbf60028a, v76
	v_add_f32_e32 v43, v59, v43
	v_exp_f32_e32 v73, v73
	v_exp_f32_e32 v100, v74
	v_mul_f32_e32 v74, 0xbf60028a, v77
	v_mul_f32_e32 v43, 0xbfb8aa3b, v43
	v_exp_f32_e32 v43, v43
	v_exp_f32_e32 v101, v74
	v_add_f32_e32 v74, 1.0, v75
	v_rcp_f32_e32 v74, v74
	v_mul_f32_e32 v48, 0xbf60028a, v48
	v_exp_f32_e32 v102, v48
	v_mul_f32_e32 v48, v81, v96
	v_mul_f32_e32 v41, v41, v49
	v_mul_f32_e64 v96, v81, -v49
	v_mul_f32_e32 v49, v48, v73
	v_add_f32_e32 v43, 1.0, v43
	v_rcp_f32_e32 v75, v48
	v_mul_f32_e32 v63, v63, v48
	v_mul_f32_e64 v73, v48, -v89
	v_mul_f32_e32 v48, v49, v83
	v_mul_f32_e32 v29, v29, v91
	v_mul_f32_e32 v28, v28, v89
	v_rcp_f32_e32 v43, v43
	v_mul_f32_e32 v59, 0xbf60028a, v74
	v_max_f32_e32 v74, 0x179abe15, v98
	v_rcp_f32_e32 v76, v49
	v_mul_f32_e32 v89, v61, v49
	v_mul_f32_e64 v91, v49, -v91
	v_mul_f32_e32 v49, v48, v82
	v_rsq_f32_e32 v74, v74
	v_mul_f32_e32 v103, v62, v81
	v_rcp_f32_e32 v77, v48
	v_mul_f32_e32 v104, v60, v48
	v_mul_f32_e64 v62, v48, -v92
	v_mul_f32_e32 v48, v49, v80
	v_rcp_f32_e32 v78, v49
	v_mul_f32_e32 v64, v64, v49
	v_mul_f32_e64 v61, v49, -v93
	v_mul_f32_e32 v49, v48, v85
	v_mul_f32_e32 v38, v38, v92
	v_mul_f32_e32 v92, v2, v49
	v_mul_f32_e32 v2, v49, v86
	v_mul_f32_e32 v43, 0xbf60028a, v43
	v_rcp_f32_e32 v79, v48
; #define GAS __attribute__((address_space(1)))
; #define LAS __attribute__((address_space(3)))
; DI unsigned cvtpk(float lo, float hi) { typedef float f2 __attribute__((ext_vector_type(2))); typedef __bf16 b2 __attribute__((ext_vector_type(2))); f2 v = {lo, hi}; b2 b = __builtin_convertvector(v, b2); return __builtin_bit_cast(unsigned, b); }
; DI unsigned short cvt1(float x) { return (unsigned short)(cvtpk(x, 0.f) & 0xffffu); }
; DI unsigned cvtpk(float lo, float hi) { typedef float f2 __attribute__((ext_vector_type(2))); typedef __bf16 b2 __attribute__((ext_vector_type(2))); f2 v = {lo, hi}; b2 b = __builtin_convertvector(v, b2); return __builtin_bit_cast(unsigned, b); }
; DI void chunk_prep(const bf16* PROJ, const float* mu, const bf16* LO, const float* pw0, const float* pa0, const float* pkk, const float* pka, const float* prk, float* SCAL, unsigned char* OPS, float* G15, LAS unsigned char* lds, int gw, int NGW, int wave, int lane) {
;     ...
; #pragma unroll
;             for (int t = 0; t < 16; ++t) { const float gm1 = g; g *= w[t]; const float inv = __builtin_amdgcn_rcpf(g); a[t] *= gm1; r[t] *= g; b[t] *= inv; k[t] *= inv; }
;         }
;         ((GAS float*)G15)[(size_t)task * 64 + d] = g;
; #pragma unroll
;         for (int t = 0; t < 16; ++t) {
;             *(LAS unsigned short*)(base + L_AT + (t * 64 + d) * 2) = cvt1(a[t]); *(LAS unsigned short*)(base + L_RT + (t * 64 + d) * 2) = cvt1(r[t]);
;             *(LAS unsigned short*)(base + L_BT + (t * 64 + d) * 2) = cvt1(b[t]); *(LAS unsigned short*)(base + L_KT + (t * 64 + d) * 2) = cvt1(k[t]); }
;         { v4u h0, h1, k0, k1;
;           h0.x = cvtpk(b[0] * g, b[1] * g); h0.y = cvtpk(b[2] * g, b[3] * g); h0.z = cvtpk(b[4] * g, b[5] * g); h0.w = cvtpk(b[6] * g, b[7] * g);
;           h1.x = cvtpk(b[8] * g, b[9] * g); h1.y = cvtpk(b[10] * g, b[11] * g); h1.z = cvtpk(b[12] * g, b[13] * g); h1.w = cvtpk(b[14] * g, b[15] * g);
;           k0.x = cvtpk(k[0] * g, k[1] * g); k0.y = cvtpk(k[2] * g, k[3] * g); k0.z = cvtpk(k[4] * g, k[5] * g); k0.w = cvtpk(k[6] * g, k[7] * g);
;           k1.x = cvtpk(k[8] * g, k[9] * g); k1.y = cvtpk(k[10] * g, k[11] * g); k1.z = cvtpk(k[12] * g, k[13] * g); k1.w = cvtpk(k[14] * g, k[15] * g);
;           *(LAS v4u*)(base + L_BH + d * 32) = h0; *(LAS v4u*)(base + L_BH + d * 32 + 16) = h1; *(LAS v4u*)(base + L_KH + d * 32) = k0; *(LAS v4u*)(base + L_KH + d * 32 + 16) = k1; }
	v_mul_f32_e32 v65, v65, v48
	v_mul_f32_e64 v60, v48, -v94
	v_mul_f32_e32 v48, v2, v84
	v_exp_f32_e32 v43, v43
	v_exp_f32_e32 v98, v59
	v_mul_f32_e32 v42, v42, v74
	v_rcp_f32_e32 v74, v81
	v_rcp_f32_e32 v80, v49
	v_rcp_f32_e32 v81, v2
	v_mul_f32_e64 v59, v49, -v95
	v_mul_f32_e32 v67, v67, v2
	v_mul_f32_e64 v49, v2, -v44
	v_mul_f32_e32 v2, v48, v97
	v_mul_f32_e32 v36, v36, v44
	v_mul_f32_e32 v44, v2, v99
	v_mul_f32_e32 v34, v34, v47
	v_rcp_f32_e32 v83, v2
	v_mul_f32_e32 v86, v71, v2
	v_mul_f32_e64 v47, v2, -v47
	v_mul_f32_e32 v2, v44, v100
	v_mul_f32_e32 v35, v35, v46
	v_mul_f32_e32 v39, v39, v93
	v_rcp_f32_e32 v84, v44
	v_mul_f32_e32 v93, v70, v44
	v_mul_f32_e64 v46, v44, -v46
	v_mul_f32_e32 v44, v2, v101
	v_mul_f32_e32 v37, v37, v45
	v_mul_f32_e32 v30, v30, v94
	v_rcp_f32_e32 v82, v48
	v_mul_f32_e32 v66, v66, v48
	v_mul_f32_e64 v48, v48, -v45
	v_rcp_f32_e32 v85, v2
	v_mul_f32_e32 v94, v69, v2
	v_mul_f32_e64 v45, v2, -v90
	v_mul_f32_e32 v2, v44, v43
	v_mul_f32_e32 v31, v31, v95
	v_mul_f32_e32 v95, v2, v98
	v_mul_f32_e32 v33, v33, v88
	v_mul_f32_e32 v32, v32, v90
	v_rcp_f32_e32 v70, v44
	v_mul_f32_e32 v90, v68, v44
	v_mul_f32_e64 v44, v44, -v88
	v_mul_f32_e32 v88, v72, v2
	v_mul_f32_e32 v72, v95, v102
	v_mul_f32_e32 v26, v26, v87
	v_mul_f32_e32 v27, v27, v42
	v_rcp_f32_e32 v68, v95
	v_mul_f32_e64 v43, v2, -v87
	v_mul_f32_e32 v87, v51, v95
	v_mul_f32_e64 v42, v95, -v42
	v_mul_f32_e32 v95, v50, v72
	v_lshl_add_u64 v[50:51], s[44:45], 0, v[8:9]
	global_store_dword v[50:51], v72, off
	v_cvt_pk_bf16_f32 v50, v103, s0
	ds_write_b16 v1, v50 offset:2048
	v_cvt_pk_bf16_f32 v50, v96, s0
	ds_write_b16 v1, v50 offset:128
	v_cvt_pk_bf16_f32 v50, v63, s0
	ds_write_b16 v1, v50 offset:2176
	v_cvt_pk_bf16_f32 v50, v73, s0
	ds_write_b16 v1, v50 offset:256
	v_cvt_pk_bf16_f32 v50, v89, s0
	ds_write_b16 v1, v50 offset:2304
	v_cvt_pk_bf16_f32 v50, v91, s0
	ds_write_b16 v1, v50 offset:384
	v_cvt_pk_bf16_f32 v50, v104, s0
	ds_write_b16 v1, v50 offset:2432
	v_cvt_pk_bf16_f32 v50, v62, s0
	ds_write_b16 v1, v50 offset:512
	v_cvt_pk_bf16_f32 v50, v64, s0
	ds_write_b16 v1, v50 offset:2560
	v_cvt_pk_bf16_f32 v50, v61, s0
	ds_write_b16 v1, v50 offset:640
	v_cvt_pk_bf16_f32 v50, v65, s0
	ds_write_b16 v1, v50 offset:2688
	v_cvt_pk_bf16_f32 v50, v60, s0
	ds_write_b16 v1, v50 offset:768
	v_cvt_pk_bf16_f32 v50, v92, s0
	ds_write_b16 v1, v50 offset:2816
	v_cvt_pk_bf16_f32 v50, v59, s0
	ds_write_b16 v1, v50 offset:896
	v_cvt_pk_bf16_f32 v50, v67, s0
	ds_write_b16 v1, v50 offset:2944
	v_cvt_pk_bf16_f32 v50, v49, s0
	ds_write_b16 v1, v50 offset:1024
	v_cvt_pk_bf16_f32 v50, v66, s0
	ds_write_b16 v1, v50 offset:3072
	v_cvt_pk_bf16_f32 v50, v48, s0
	ds_write_b16 v1, v50 offset:1152
	v_cvt_pk_bf16_f32 v50, v86, s0
	ds_write_b16 v1, v50 offset:3200
	v_cvt_pk_bf16_f32 v50, v47, s0
	ds_write_b16 v1, v50 offset:1280
	v_cvt_pk_bf16_f32 v50, v93, s0
	ds_write_b16 v1, v50 offset:3328
	v_cvt_pk_bf16_f32 v50, v46, s0
	ds_write_b16 v1, v50 offset:1408
	v_cvt_pk_bf16_f32 v50, v94, s0
	ds_write_b16 v1, v50 offset:3456
	v_cvt_pk_bf16_f32 v50, v45, s0
	ds_write_b16 v1, v50 offset:1536
	v_cvt_pk_bf16_f32 v50, v90, s0
	ds_write_b16 v1, v50 offset:3584
	v_cvt_pk_bf16_f32 v50, v44, s0
	ds_write_b16 v1, v50 offset:1664
	v_cvt_pk_bf16_f32 v50, v88, s0
	ds_write_b16 v1, v50 offset:3712
	v_cvt_pk_bf16_f32 v50, v43, s0
	ds_write_b16 v1, v50 offset:1792
	v_cvt_pk_bf16_f32 v50, v87, s0
	v_mul_f32_e32 v40, v40, v10
	ds_write_b16 v1, v50 offset:3840
	v_cvt_pk_bf16_f32 v50, v42, s0
	ds_write_b16 v1, v50 offset:1920
	v_cvt_pk_bf16_f32 v50, v95, s0
	v_pk_mul_f32 v[40:41], v[74:75], v[40:41]
	ds_write_b16 v1, v50 offset:3968
	v_cvt_pk_bf16_f32 v50, v40, s0
	ds_write_b16 v1, v50 offset:4096
	v_cvt_pk_bf16_f32 v50, v41, s0
	v_pk_mul_f32 v[40:41], v[72:73], v[40:41] op_sel_hi:[0,1]
	v_pk_mul_f32 v[28:29], v[76:77], v[28:29]
	v_cvt_pk_bf16_f32 v64, v40, v41
	v_cvt_pk_bf16_f32 v40, v28, s0
	ds_write_b16 v1, v40 offset:4352
	v_cvt_pk_bf16_f32 v40, v29, s0
	v_pk_mul_f32 v[28:29], v[72:73], v[28:29] op_sel_hi:[0,1]
	v_cvt_pk_bf16_f32 v65, v28, v29
	v_pk_mul_f32 v[28:29], v[78:79], v[38:39]
	v_rcp_f32_e32 v71, v2
	v_cvt_pk_bf16_f32 v38, v28, s0
	ds_write_b16 v1, v38 offset:4608
	v_cvt_pk_bf16_f32 v38, v29, s0
	v_pk_mul_f32 v[28:29], v[72:73], v[28:29] op_sel_hi:[0,1]
	v_cvt_pk_bf16_f32 v66, v28, v29
	v_pk_mul_f32 v[28:29], v[80:81], v[30:31]
	v_rcp_f32_e32 v69, v72
	v_cvt_pk_bf16_f32 v30, v28, s0
	ds_write_b16 v1, v30 offset:4864
	v_cvt_pk_bf16_f32 v30, v29, s0
	v_pk_mul_f32 v[28:29], v[72:73], v[28:29] op_sel_hi:[0,1]
	v_cvt_pk_bf16_f32 v67, v28, v29
	v_pk_mul_f32 v[28:29], v[82:83], v[36:37]
	ds_write_b16 v1, v30 offset:4992
	v_cvt_pk_bf16_f32 v30, v28, s0
	ds_write_b16 v1, v30 offset:5120
	v_cvt_pk_bf16_f32 v30, v29, s0
	ds_write_b16 v1, v30 offset:5248
	v_pk_mul_f32 v[28:29], v[72:73], v[28:29] op_sel_hi:[0,1]
	v_pk_mul_f32 v[30:31], v[84:85], v[34:35]
	v_cvt_pk_bf16_f32 v28, v28, v29
	v_cvt_pk_bf16_f32 v29, v30, s0
	ds_write_b16 v1, v29 offset:5376
	v_cvt_pk_bf16_f32 v29, v31, s0
	v_pk_mul_f32 v[30:31], v[72:73], v[30:31] op_sel_hi:[0,1]
	ds_write_b16 v1, v29 offset:5504
	v_cvt_pk_bf16_f32 v29, v30, v31
	v_pk_mul_f32 v[30:31], v[70:71], v[32:33]
	v_pk_mul_f32 v[26:27], v[68:69], v[26:27]
	v_cvt_pk_bf16_f32 v32, v30, s0
	ds_write_b16 v1, v32 offset:5632
	v_cvt_pk_bf16_f32 v32, v31, s0
	v_pk_mul_f32 v[30:31], v[72:73], v[30:31] op_sel_hi:[0,1]
	v_cvt_pk_bf16_f32 v30, v30, v31
	v_cvt_pk_bf16_f32 v31, v26, s0
	ds_write_b16 v1, v31 offset:5888
	v_cvt_pk_bf16_f32 v31, v27, s0
	v_pk_mul_f32 v[26:27], v[72:73], v[26:27] op_sel_hi:[0,1]
	v_pk_mul_f32 v[4:5], v[74:75], v[4:5]
	ds_write_b16 v1, v31 offset:6016
; #define LAS __attribute__((address_space(3)))
; DI void chunk_prep(const bf16* PROJ, const float* mu, const bf16* LO, const float* pw0, const float* pa0, const float* pkk, const float* pka, const float* prk, float* SCAL, unsigned char* OPS, float* G15, LAS unsigned char* lds, int gw, int NGW, int wave, int lane) {
;     ...
;         { v4u h0, h1, k0, k1;
;           h0.x = cvtpk(b[0] * g, b[1] * g); h0.y = cvtpk(b[2] * g, b[3] * g); h0.z = cvtpk(b[4] * g, b[5] * g); h0.w = cvtpk(b[6] * g, b[7] * g);
;           h1.x = cvtpk(b[8] * g, b[9] * g); h1.y = cvtpk(b[10] * g, b[11] * g); h1.z = cvtpk(b[12] * g, b[13] * g); h1.w = cvtpk(b[14] * g, b[15] * g);
;           k0.x = cvtpk(k[0] * g, k[1] * g); k0.y = cvtpk(k[2] * g, k[3] * g); k0.z = cvtpk(k[4] * g, k[5] * g); k0.w = cvtpk(k[6] * g, k[7] * g);
;           k1.x = cvtpk(k[8] * g, k[9] * g); k1.y = cvtpk(k[10] * g, k[11] * g); k1.z = cvtpk(k[12] * g, k[13] * g); k1.w = cvtpk(k[14] * g, k[15] * g);
;           *(LAS v4u*)(base + L_BH + d * 32) = h0; *(LAS v4u*)(base + L_BH + d * 32 + 16) = h1; *(LAS v4u*)(base + L_KH + d * 32) = k0; *(LAS v4u*)(base + L_KH + d * 32 + 16) = k1; }
;         CS_LWAIT();
;         { f4 gab = {0.f, 0.f, 0.f, 0.f}, gak = gab, grb = gab, grk = gab;
; #pragma unroll
;           for (int kb = 0; kb < 2; ++kb) { const int fo = (x * 64 + 32 * kb + 8 * q) * 2;
;               const bf16x8 fa = *(const LAS bf16x8*)(base + L_AT + fo), fr = *(const LAS bf16x8*)(base + L_RT + fo), fb = *(const LAS bf16x8*)(base + L_BT + fo), fk = *(const LAS bf16x8*)(base + L_KT + fo);
;               gab = CS_MFMA(fb, fa, gab); gak = CS_MFMA(fk, fa, gak); grb = CS_MFMA(fb, fr, grb); grk = CS_MFMA(fk, fr, grk); }
; #pragma unroll
;           for (int rr = 0; rr < 4; ++rr) { const int u = 4 * q + rr; if (!(u < x)) { gab[rr] = 0.f; gak[rr] = 0.f; } if (!(u <= x)) { grb[rr] = 0.f; grk[rr] = 0.f; } }
;           const int go = (x * 16 + 4 * q) * 4;
;           *(LAS f4*)(base + L_AB + go) = gab; *(LAS f4*)(base + L_AK + go) = gak; *(LAS f4*)(base + L_RB + go) = grb; *(LAS f4*)(base + L_RK + go) = grk; }
;         CS_LWAIT();
;         float mm[16];
; #pragma unroll
;         for (int t = 0; t < 16; ++t) mm[t] = *(const LAS float*)(base + L_AK + (t * 16 + x) * 4);
; #pragma unroll
;         for (int t = 1; t < 16; ++t) {
;             float ab[16];
; #pragma unroll
	v_cvt_pk_bf16_f32 v31, v26, v27
	v_cvt_pk_bf16_f32 v26, v4, s0
	ds_write_b16 v1, v26 offset:6144
	v_cvt_pk_bf16_f32 v26, v5, s0
	v_pk_mul_f32 v[4:5], v[4:5], v[72:73] op_sel_hi:[1,0]
	ds_write_b16 v1, v32 offset:5760
	v_cvt_pk_bf16_f32 v32, v4, v5
	v_pk_mul_f32 v[4:5], v[76:77], v[12:13]
	v_cvt_pk_bf16_f32 v2, -v10, s0
	v_cvt_pk_bf16_f32 v12, v4, s0
	ds_write_b16 v1, v12 offset:6400
	v_cvt_pk_bf16_f32 v12, v5, s0
	v_pk_mul_f32 v[4:5], v[4:5], v[72:73] op_sel_hi:[1,0]
	ds_write_b16 v1, v12 offset:6528
	v_cvt_pk_bf16_f32 v33, v4, v5
	v_pk_mul_f32 v[4:5], v[78:79], v[14:15]
	ds_write_b16 v1, v2
	v_cvt_pk_bf16_f32 v12, v4, s0
	ds_write_b16 v1, v12 offset:6656
	v_cvt_pk_bf16_f32 v12, v5, s0
	v_pk_mul_f32 v[4:5], v[4:5], v[72:73] op_sel_hi:[1,0]
	ds_write_b16 v1, v12 offset:6784
	v_cvt_pk_bf16_f32 v34, v4, v5
	v_pk_mul_f32 v[4:5], v[80:81], v[16:17]
	ds_write_b16 v1, v50 offset:4224
	v_cvt_pk_bf16_f32 v12, v4, s0
	ds_write_b16 v1, v12 offset:6912
	v_cvt_pk_bf16_f32 v12, v5, s0
	v_pk_mul_f32 v[4:5], v[4:5], v[72:73] op_sel_hi:[1,0]
	ds_write_b16 v1, v12 offset:7040
	v_cvt_pk_bf16_f32 v35, v4, v5
	v_pk_mul_f32 v[4:5], v[82:83], v[18:19]
	ds_write_b16 v1, v40 offset:4480
	v_cvt_pk_bf16_f32 v12, v4, s0
	ds_write_b16 v1, v12 offset:7168
	v_cvt_pk_bf16_f32 v12, v5, s0
	v_pk_mul_f32 v[4:5], v[4:5], v[72:73] op_sel_hi:[1,0]
	ds_write_b16 v1, v12 offset:7296
	v_cvt_pk_bf16_f32 v12, v4, v5
	v_pk_mul_f32 v[4:5], v[84:85], v[20:21]
	ds_write_b16 v1, v38 offset:4736
	v_cvt_pk_bf16_f32 v13, v4, s0
	ds_write_b16 v1, v13 offset:7424
	v_cvt_pk_bf16_f32 v13, v5, s0
	v_pk_mul_f32 v[4:5], v[4:5], v[72:73] op_sel_hi:[1,0]
	ds_write_b16 v1, v13 offset:7552
	v_cvt_pk_bf16_f32 v13, v4, v5
	v_pk_mul_f32 v[4:5], v[70:71], v[22:23]
	ds_write_b16 v1, v26 offset:6272
	v_cvt_pk_bf16_f32 v14, v4, s0
	ds_write_b16 v1, v14 offset:7680
	v_cvt_pk_bf16_f32 v14, v5, s0
	v_pk_mul_f32 v[4:5], v[4:5], v[72:73] op_sel_hi:[1,0]
	ds_write_b16 v1, v14 offset:7808
	v_cvt_pk_bf16_f32 v14, v4, v5
	v_pk_mul_f32 v[4:5], v[68:69], v[24:25]
	s_or_b64 vcc, s[16:17], s[4:5]
	v_cvt_pk_bf16_f32 v15, v4, s0
	ds_write_b16 v1, v15 offset:7936
	v_cvt_pk_bf16_f32 v15, v5, s0
	v_pk_mul_f32 v[4:5], v[72:73], v[4:5] op_sel_hi:[0,1]
	ds_write_b16 v1, v15 offset:8064
	v_cvt_pk_bf16_f32 v15, v4, v5
	ds_write_b128 v53, v[64:67] offset:8192
	ds_write_b128 v53, v[28:31] offset:8208
	ds_write_b128 v53, v[32:35] offset:10240
	ds_write_b128 v53, v[12:15] offset:10256
	s_waitcnt lgkmcnt(0)
	ds_read_b128 v[12:15], v54 offset:4096
	ds_read_b128 v[16:19], v54
	ds_read_b128 v[20:23], v54 offset:64
	ds_read_b128 v[24:27], v54 offset:4160
	ds_read_b128 v[32:35], v54 offset:6144
	ds_read_b128 v[36:39], v54 offset:6208
	ds_read_b128 v[64:67], v54 offset:2048
	ds_read_b128 v[68:71], v54 offset:2112
	s_waitcnt lgkmcnt(6)
	v_mfma_f32_16x16x32_bf16 v[28:31], v[12:15], v[16:19], 0
	v_mov_b32_e32 v4, s52
	s_mov_b32 s42, 0x87100000
	v_readlane_b32 s50, v254, 7
	s_waitcnt lgkmcnt(1)
	v_mfma_f32_16x16x32_bf16 v[12:15], v[12:15], v[64:67], 0
	s_add_i32 s54, s54, s50
	s_add_u32 s38, s38, s40
	s_addc_u32 s39, s39, s41
	v_mfma_f32_16x16x32_bf16 v[16:19], v[32:35], v[16:19], 0
	s_cmpk_lt_i32 s54, 0x4000
	v_lshl_add_u64 v[8:9], v[8:9], 0, s[36:37]
	v_readlane_b32 s51, v254, 8
	v_mfma_f32_16x16x32_bf16 v[32:35], v[32:35], v[64:67], 0
	s_waitcnt lgkmcnt(0)
	v_mfma_f32_16x16x32_bf16 v[12:15], v[24:27], v[68:71], v[12:15]
	v_mfma_f32_16x16x32_bf16 v[28:31], v[24:27], v[20:23], v[28:31]
	v_mov_b32_e32 v26, s52
	v_mov_b32_e32 v24, s52
	s_nop 4
	v_cndmask_b32_e64 v25, v12, v26, s[6:7]
	v_mfma_f32_16x16x32_bf16 v[16:19], v[36:39], v[20:23], v[16:19]
	v_cndmask_b32_e64 v12, v25, v12, s[4:5]
	v_cndmask_b32_e64 v26, 0, v30, s[8:9]
	v_cndmask_b32_e64 v25, 0, v29, s[16:17]
	v_mfma_f32_16x16x32_bf16 v[20:23], v[36:39], v[68:71], v[32:35]
	v_cndmask_b32_e64 v27, 0, v31, s[12:13]
	s_nop 2
	v_cndmask_b32_e32 v16, v24, v16, vcc
	v_cndmask_b32_e32 v24, v4, v28, vcc
	v_mov_b32_e32 v32, s52
	v_cndmask_b32_e64 v13, 0, v13, s[4:5]
	v_cndmask_b32_e64 v5, v20, v32, s[6:7]
	v_cndmask_b32_e64 v20, v5, v20, s[4:5]
	v_cndmask_b32_e64 v21, 0, v21, s[4:5]
	v_cndmask_b32_e64 v18, 0, v18, s[8:9]
	v_cndmask_b32_e64 v17, 0, v17, s[16:17]
	v_cndmask_b32_e64 v22, v22, 0, s[10:11]
	v_cndmask_b32_e64 v14, v14, 0, s[10:11]
	v_cndmask_b32_e64 v19, 0, v19, s[12:13]
	v_cndmask_b32_e64 v23, v23, 0, s[14:15]
	v_cndmask_b32_e64 v15, v15, 0, s[14:15]
	ds_write_b128 v55, v[24:27] offset:12288
	ds_write_b128 v55, v[16:19] offset:13312
	ds_write_b128 v55, v[12:15] offset:14336
	ds_write_b128 v55, v[20:23] offset:15360
	s_waitcnt lgkmcnt(0)
	v_add_u32_e32 v26, 0x3400, v56
	v_mov_b32_e32 v29, s53
	ds_read2_b32 v[22:23], v26 offset1:16
	ds_read2_b32 v[18:19], v26 offset0:32 offset1:48
	ds_read2_b32 v[14:15], v26 offset0:64 offset1:80
	ds_read2_b32 v[12:13], v26 offset0:96 offset1:112
	ds_read2_b32 v[4:5], v26 offset0:128 offset1:144
	ds_read_b128 v[30:33], v29 offset:12352
	ds_read2_b32 v[16:17], v26 offset0:160 offset1:176
	s_waitcnt lgkmcnt(1)
	ds_read_b128 v[32:35], v29 offset:12416
	ds_read2_b32 v[24:25], v26 offset0:192 offset1:208
	ds_read2_b32 v[20:21], v26 offset0:224 offset1:240
	s_waitcnt lgkmcnt(2)
	ds_read_b128 v[34:37], v29 offset:12480
	ds_read_b128 v[38:41], v29 offset:12544
	v_fma_f32 v27, -v10, v30, v96
	v_fma_f32 v23, v22, v30, v23
	v_fma_f32 v28, -v10, v32, v73
	v_fma_f32 v18, v22, v32, v18
	s_waitcnt lgkmcnt(1)
	v_fma_f32 v30, -v10, v34, v91
	v_fmac_f32_e32 v19, v22, v34
	v_fmac_f32_e32 v28, v27, v33
	v_fmac_f32_e32 v18, v23, v33
	v_fmac_f32_e32 v30, v27, v35
	v_fmac_f32_e32 v19, v23, v35
	v_fmac_f32_e32 v30, v28, v36
	v_fmac_f32_e32 v19, v18, v36
	ds_read_b128 v[34:37], v29 offset:12608
	s_waitcnt lgkmcnt(1)
; #define LAS __attribute__((address_space(3)))
; DI void chunk_prep(const bf16* PROJ, const float* mu, const bf16* LO, const float* pw0, const float* pa0, const float* pkk, const float* pka, const float* prk, float* SCAL, unsigned char* OPS, float* G15, LAS unsigned char* lds, int gw, int NGW, int wave, int lane) {
;     ...
; #pragma unroll
;         for (int t = 1; t < 16; ++t) {
;             float ab[16];
; #pragma unroll
;             for (int u4 = 0; u4 < 4; ++u4) if (4 * u4 < t) { const f4 v = *(const LAS f4*)(base + L_AB + (t * 16 + 4 * u4) * 4); ab[4 * u4] = v.x; ab[4 * u4 + 1] = v.y; ab[4 * u4 + 2] = v.z; ab[4 * u4 + 3] = v.w; }
; #pragma unroll
;             for (int u = 0; u < 16; ++u) if (u < t) { a[t] = fmaf(a[u], ab[u], a[t]); mm[t] = fmaf(mm[u], ab[u], mm[t]); }
;         }
	v_fma_f32 v31, -v10, v38, v62
	v_fma_f32 v14, v22, v38, v14
	v_fmac_f32_e32 v31, v27, v39
	v_fmac_f32_e32 v14, v23, v39
	v_fmac_f32_e32 v31, v28, v40
	v_fmac_f32_e32 v14, v18, v40
	v_fmac_f32_e32 v31, v30, v41
	v_fmac_f32_e32 v14, v19, v41
	ds_read_b128 v[38:41], v29 offset:12624
	s_waitcnt lgkmcnt(1)
	v_fma_f32 v32, -v10, v34, v61
	v_fmac_f32_e32 v15, v22, v34
	ds_read_b128 v[62:65], v29 offset:12672
	v_fmac_f32_e32 v32, v27, v35
	v_fmac_f32_e32 v15, v23, v35
	v_fmac_f32_e32 v32, v28, v36
	v_fmac_f32_e32 v15, v18, v36
	v_fmac_f32_e32 v32, v30, v37
	v_fmac_f32_e32 v15, v19, v37
	ds_read_b128 v[34:37], v29 offset:12688
	s_waitcnt lgkmcnt(2)
	v_fmac_f32_e32 v32, v31, v38
	v_fmac_f32_e32 v15, v14, v38
	s_waitcnt lgkmcnt(0)
	ds_read_b128 v[36:39], v29 offset:12736
	v_fma_f32 v33, -v10, v62, v60
	v_fma_f32 v12, v22, v62, v12
	v_fmac_f32_e32 v33, v27, v63
	v_fmac_f32_e32 v12, v23, v63
	v_fmac_f32_e32 v33, v28, v64
	v_fmac_f32_e32 v12, v18, v64
	v_fmac_f32_e32 v33, v30, v65
	v_fmac_f32_e32 v12, v19, v65
	v_fmac_f32_e32 v33, v31, v34
	v_fmac_f32_e32 v12, v14, v34
	ds_read_b128 v[60:63], v29 offset:12752
	s_waitcnt lgkmcnt(1)
	v_fma_f32 v34, -v10, v36, v59
	v_fmac_f32_e32 v13, v22, v36
	v_fmac_f32_e32 v34, v27, v37
	v_fmac_f32_e32 v13, v23, v37
	v_fmac_f32_e32 v34, v28, v38
	v_fmac_f32_e32 v13, v18, v38
	v_fmac_f32_e32 v34, v30, v39
	v_fmac_f32_e32 v13, v19, v39
	ds_read_b128 v[36:39], v29 offset:12800
	s_waitcnt lgkmcnt(1)
	v_fmac_f32_e32 v34, v31, v60
	v_fmac_f32_e32 v13, v14, v60
	v_fmac_f32_e32 v33, v32, v35
	v_fmac_f32_e32 v12, v15, v35
	v_fmac_f32_e32 v34, v32, v61
	v_fmac_f32_e32 v13, v15, v61
	v_fmac_f32_e32 v34, v33, v62
	v_fmac_f32_e32 v13, v12, v62
	ds_read_b128 v[60:63], v29 offset:12816
	s_waitcnt lgkmcnt(1)
	v_fma_f32 v35, -v10, v36, v49
	v_fma_f32 v4, v22, v36, v4
	v_fmac_f32_e32 v35, v27, v37
	v_fmac_f32_e32 v4, v23, v37
	v_fmac_f32_e32 v35, v28, v38
	v_fmac_f32_e32 v4, v18, v38
	v_fmac_f32_e32 v35, v30, v39
	v_fmac_f32_e32 v4, v19, v39
	ds_read_b128 v[36:39], v29 offset:12864
	s_waitcnt lgkmcnt(1)
	v_fmac_f32_e32 v35, v31, v60
	v_fmac_f32_e32 v4, v14, v60
	v_fmac_f32_e32 v35, v32, v61
	v_fmac_f32_e32 v4, v15, v61
	v_fmac_f32_e32 v35, v33, v62
	v_fmac_f32_e32 v4, v12, v62
	s_waitcnt lgkmcnt(0)
	v_fma_f32 v40, -v10, v36, v48
	v_fmac_f32_e32 v5, v22, v36
	v_fmac_f32_e32 v35, v34, v63
	v_fmac_f32_e32 v4, v13, v63
	ds_read_b128 v[60:63], v29 offset:12880
	ds_read_b128 v[64:67], v29 offset:12896
	v_fmac_f32_e32 v40, v27, v37
	v_fmac_f32_e32 v5, v23, v37
	v_fmac_f32_e32 v40, v28, v38
	v_fmac_f32_e32 v5, v18, v38
	v_fmac_f32_e32 v40, v30, v39
	v_fmac_f32_e32 v5, v19, v39
	ds_read_b128 v[36:39], v29 offset:12928
	s_waitcnt lgkmcnt(2)
	v_fmac_f32_e32 v40, v31, v60
	v_fmac_f32_e32 v5, v14, v60
	v_fmac_f32_e32 v40, v32, v61
	v_fmac_f32_e32 v5, v15, v61
	v_fmac_f32_e32 v40, v33, v62
	v_fmac_f32_e32 v5, v12, v62
	v_fmac_f32_e32 v40, v34, v63
	v_fmac_f32_e32 v5, v13, v63
	ds_read_b128 v[48:51], v29 offset:12944
	ds_read_b128 v[60:63], v29 offset:12960
	s_waitcnt lgkmcnt(2)
	v_fma_f32 v41, -v10, v36, v47
	v_fma_f32 v16, v22, v36, v16
	v_fmac_f32_e32 v41, v27, v37
	v_fmac_f32_e32 v16, v23, v37
	v_fmac_f32_e32 v41, v28, v38
	v_fmac_f32_e32 v16, v18, v38
	v_fmac_f32_e32 v41, v30, v39
	v_fmac_f32_e32 v16, v19, v39
	s_waitcnt lgkmcnt(1)
	v_fmac_f32_e32 v41, v31, v48
	v_fmac_f32_e32 v16, v14, v48
	ds_read_b128 v[36:39], v29 offset:12992
	v_fmac_f32_e32 v41, v32, v49
	v_fmac_f32_e32 v16, v15, v49
	v_fmac_f32_e32 v41, v33, v50
	v_fmac_f32_e32 v16, v12, v50
	v_fmac_f32_e32 v41, v34, v51
	v_fmac_f32_e32 v16, v13, v51
	v_fmac_f32_e32 v40, v35, v64
	v_fmac_f32_e32 v5, v4, v64
	s_waitcnt lgkmcnt(1)
	v_fmac_f32_e32 v41, v35, v60
	v_fmac_f32_e32 v16, v4, v60
	v_fmac_f32_e32 v41, v40, v61
	v_fmac_f32_e32 v16, v5, v61
	ds_read_b128 v[48:51], v29 offset:13008
	ds_read_b128 v[60:63], v29 offset:13024
	s_waitcnt lgkmcnt(2)
	v_fma_f32 v59, -v10, v36, v46
	v_fmac_f32_e32 v17, v22, v36
	v_fmac_f32_e32 v59, v27, v37
	v_fmac_f32_e32 v17, v23, v37
	v_fmac_f32_e32 v59, v28, v38
	v_fmac_f32_e32 v17, v18, v38
	v_fmac_f32_e32 v59, v30, v39
	v_fmac_f32_e32 v17, v19, v39
	s_waitcnt lgkmcnt(1)
	v_fmac_f32_e32 v59, v31, v48
	v_fmac_f32_e32 v17, v14, v48
	v_fmac_f32_e32 v59, v32, v49
	v_fmac_f32_e32 v17, v15, v49
	ds_read_b128 v[36:39], v29 offset:13056
	v_fmac_f32_e32 v59, v33, v50
	v_fmac_f32_e32 v17, v12, v50
	v_fmac_f32_e32 v59, v34, v51
	v_fmac_f32_e32 v17, v13, v51
	s_waitcnt lgkmcnt(1)
	v_fmac_f32_e32 v59, v35, v60
	v_fmac_f32_e32 v17, v4, v60
	v_fmac_f32_e32 v59, v40, v61
	v_fmac_f32_e32 v17, v5, v61
	v_fmac_f32_e32 v59, v41, v62
	v_fmac_f32_e32 v17, v16, v62
	ds_read_b128 v[46:49], v29 offset:13072
	ds_read_b128 v[60:63], v29 offset:13088
	s_waitcnt lgkmcnt(2)
	v_fma_f32 v68, -v10, v36, v45
	v_fma_f32 v24, v22, v36, v24
	v_fmac_f32_e32 v68, v27, v37
	v_fmac_f32_e32 v24, v23, v37
	v_fmac_f32_e32 v68, v28, v38
	v_fmac_f32_e32 v24, v18, v38
	v_fmac_f32_e32 v68, v30, v39
	v_fmac_f32_e32 v24, v19, v39
	s_waitcnt lgkmcnt(1)
	v_fmac_f32_e32 v68, v31, v46
	v_fmac_f32_e32 v24, v14, v46
	v_fmac_f32_e32 v68, v32, v47
	v_fmac_f32_e32 v24, v15, v47
	v_fmac_f32_e32 v68, v33, v48
	v_fmac_f32_e32 v24, v12, v48
	v_fmac_f32_e32 v68, v34, v49
	v_fmac_f32_e32 v24, v13, v49
	ds_read_b128 v[36:39], v29 offset:13120
	s_waitcnt lgkmcnt(1)
; #define GAS __attribute__((address_space(1)))
; #define LAS __attribute__((address_space(3)))
; DI unsigned short cvt1(float x) { return (unsigned short)(cvtpk(x, 0.f) & 0xffffu); }
; DI void chunk_prep(const bf16* PROJ, const float* mu, const bf16* LO, const float* pw0, const float* pa0, const float* pkk, const float* pka, const float* prk, float* SCAL, unsigned char* OPS, float* G15, LAS unsigned char* lds, int gw, int NGW, int wave, int lane) {
;     ...
; #pragma unroll
;         for (int t = 1; t < 16; ++t) {
;             float ab[16];
; #pragma unroll
;             for (int u4 = 0; u4 < 4; ++u4) if (4 * u4 < t) { const f4 v = *(const LAS f4*)(base + L_AB + (t * 16 + 4 * u4) * 4); ab[4 * u4] = v.x; ab[4 * u4 + 1] = v.y; ab[4 * u4 + 2] = v.z; ab[4 * u4 + 3] = v.w; }
; #pragma unroll
;             for (int u = 0; u < 16; ++u) if (u < t) { a[t] = fmaf(a[u], ab[u], a[t]); mm[t] = fmaf(mm[u], ab[u], mm[t]); }
;         }
;         CS_LWAIT();
; #pragma unroll
;         for (int t = 0; t < 16; ++t) { *(LAS unsigned short*)(base + L_AT + (t * 64 + d) * 2) = cvt1(a[t]); *(LAS float*)(base + L_AK + (t * 16 + x) * 4) = mm[t]; }
;         CS_LWAIT();
;         unsigned char* ob = OPS + (size_t)task * OPS_TASK + lane * 16;
; #pragma unroll
;         for (int kb = 0; kb < 2; ++kb) { const int fo = (x * 64 + 32 * kb + 4 * q) * 2;
;             const v2u w0 = *(const LAS v2u*)(base + L_AT + fo), w1 = *(const LAS v2u*)(base + L_AT + fo + 32), r0 = *(const LAS v2u*)(base + L_RT + fo), r1 = *(const LAS v2u*)(base + L_RT + fo + 32);
;             *(GAS v4u*)(ob + kb * 1024) = (v4u){w0.x, w0.y, w1.x, w1.y}; *(GAS v4u*)(ob + (3 + kb) * 1024) = (v4u){r0.x, r0.y, r1.x, r1.y}; }
;         { const int go = (x * 16 + 4 * q) * 4; const f4 m2 = *(const LAS f4*)(base + L_AK + go), rb = *(const LAS f4*)(base + L_RB + go), rk = *(const LAS f4*)(base + L_RK + go);
;           *(GAS v4u*)(ob + 2 * 1024) = (v4u){0u, 0u, cvtpk(m2.x, m2.y), cvtpk(m2.z, m2.w)};
;           *(GAS v4u*)(ob + 5 * 1024) = (v4u){cvtpk(rb.x, rb.y), cvtpk(rb.z, rb.w), cvtpk(rk.x, rk.y), cvtpk(rk.z, rk.w)}; }
; #pragma unroll
;         for (int dt = 0; dt < 4; ++dt) { const int fo = ((16 * dt + x) * 16 + 4 * q) * 2; const v2u h = *(const LAS v2u*)(base + L_BH + fo), kk = *(const LAS v2u*)(base + L_KH + fo);
;             *(GAS v4u*)(ob + (6 + dt) * 1024) = (v4u){h.x, h.y, kk.x, kk.y}; }
	v_fmac_f32_e32 v68, v35, v60
	v_fmac_f32_e32 v24, v4, v60
	v_fmac_f32_e32 v68, v40, v61
	v_fmac_f32_e32 v24, v5, v61
	v_fmac_f32_e32 v68, v41, v62
	v_fmac_f32_e32 v24, v16, v62
	v_fmac_f32_e32 v68, v59, v63
	v_fmac_f32_e32 v24, v17, v63
	ds_read_b128 v[46:49], v29 offset:13136
	ds_read_b128 v[60:63], v29 offset:13152
	ds_read_b128 v[64:67], v29 offset:13168
	s_waitcnt lgkmcnt(0)
	v_fma_f32 v65, -v10, v36, v44
	v_fmac_f32_e32 v25, v22, v36
	v_fmac_f32_e32 v65, v27, v37
	v_fmac_f32_e32 v25, v23, v37
	v_fmac_f32_e32 v65, v28, v38
	v_fmac_f32_e32 v25, v18, v38
	v_fmac_f32_e32 v65, v30, v39
	v_fmac_f32_e32 v25, v19, v39
	v_fmac_f32_e32 v65, v31, v46
	v_fmac_f32_e32 v25, v14, v46
	v_fmac_f32_e32 v65, v32, v47
	v_fmac_f32_e32 v25, v15, v47
	ds_read_b128 v[36:39], v29 offset:13184
	v_fmac_f32_e32 v65, v33, v48
	v_fmac_f32_e32 v25, v12, v48
	v_fmac_f32_e32 v65, v34, v49
	v_fmac_f32_e32 v25, v13, v49
	v_fmac_f32_e32 v65, v35, v60
	v_fmac_f32_e32 v25, v4, v60
	v_fmac_f32_e32 v65, v40, v61
	v_fmac_f32_e32 v25, v5, v61
	v_fmac_f32_e32 v65, v41, v62
	v_fmac_f32_e32 v25, v16, v62
	s_waitcnt lgkmcnt(0)
	v_fma_f32 v43, -v10, v36, v43
	v_fma_f32 v20, v22, v36, v20
	v_fmac_f32_e32 v65, v59, v63
	v_fmac_f32_e32 v25, v17, v63
	ds_read_b128 v[44:47], v29 offset:13200
	ds_read_b128 v[48:51], v29 offset:13216
	ds_read_b128 v[60:63], v29 offset:13232
	v_fmac_f32_e32 v43, v27, v37
	v_fmac_f32_e32 v20, v23, v37
	v_fmac_f32_e32 v43, v28, v38
	v_fmac_f32_e32 v20, v18, v38
	v_fmac_f32_e32 v43, v30, v39
	v_fmac_f32_e32 v20, v19, v39
	s_waitcnt lgkmcnt(2)
	v_fmac_f32_e32 v43, v31, v44
	v_fmac_f32_e32 v20, v14, v44
	v_fmac_f32_e32 v43, v32, v45
	v_fmac_f32_e32 v20, v15, v45
	v_fmac_f32_e32 v43, v33, v46
	v_fmac_f32_e32 v20, v12, v46
	v_fmac_f32_e32 v43, v34, v47
	v_fmac_f32_e32 v20, v13, v47
	ds_read_b128 v[36:39], v29 offset:13248
	s_waitcnt lgkmcnt(2)
	v_fmac_f32_e32 v43, v35, v48
	v_fmac_f32_e32 v20, v4, v48
	v_fmac_f32_e32 v43, v40, v49
	v_fmac_f32_e32 v20, v5, v49
	v_fmac_f32_e32 v43, v41, v50
	v_fmac_f32_e32 v20, v16, v50
	v_fmac_f32_e32 v43, v59, v51
	v_fmac_f32_e32 v20, v17, v51
	v_fmac_f32_e32 v65, v68, v64
	v_fmac_f32_e32 v25, v24, v64
	s_waitcnt lgkmcnt(1)
	v_fmac_f32_e32 v43, v68, v60
	v_fmac_f32_e32 v20, v24, v60
	s_waitcnt lgkmcnt(0)
	v_fma_f32 v10, -v10, v36, v42
	v_fmac_f32_e32 v43, v65, v61
	v_fmac_f32_e32 v20, v25, v61
	ds_read_b128 v[44:47], v29 offset:13264
	ds_read_b128 v[48:51], v29 offset:13280
	ds_read_b128 v[60:63], v29 offset:13296
	v_fmac_f32_e32 v10, v27, v37
	s_waitcnt lgkmcnt(0)
	ds_write_b16 v1, v2
	v_cvt_pk_bf16_f32 v2, v27, s0
	v_fmac_f32_e32 v21, v22, v36
	v_fmac_f32_e32 v10, v28, v38
	ds_write_b16 v1, v2 offset:128
	ds_write2_b32 v26, v22, v23 offset1:16
	v_cvt_pk_bf16_f32 v2, v28, s0
	v_fmac_f32_e32 v21, v23, v37
	v_fmac_f32_e32 v10, v30, v39
	ds_write_b16 v1, v2 offset:256
	v_cvt_pk_bf16_f32 v2, v30, s0
	v_fmac_f32_e32 v21, v18, v38
	s_waitcnt lgkmcnt(6)
	v_fmac_f32_e32 v10, v31, v44
	ds_write_b16 v1, v2 offset:384
	ds_write2_b32 v26, v18, v19 offset0:32 offset1:48
	v_cvt_pk_bf16_f32 v2, v31, s0
	v_fmac_f32_e32 v21, v19, v39
	v_fmac_f32_e32 v10, v32, v45
	ds_write_b16 v1, v2 offset:512
	v_cvt_pk_bf16_f32 v2, v32, s0
	v_fmac_f32_e32 v21, v14, v44
	v_fmac_f32_e32 v10, v33, v46
	ds_write_b16 v1, v2 offset:640
	ds_write2_b32 v26, v14, v15 offset0:64 offset1:80
	v_cvt_pk_bf16_f32 v2, v33, s0
	v_fmac_f32_e32 v21, v15, v45
	v_fmac_f32_e32 v10, v34, v47
	ds_write_b16 v1, v2 offset:768
	v_cvt_pk_bf16_f32 v2, v34, s0
	v_fmac_f32_e32 v21, v12, v46
	s_waitcnt lgkmcnt(11)
	v_fmac_f32_e32 v10, v35, v48
	ds_write_b16 v1, v2 offset:896
	ds_write2_b32 v26, v12, v13 offset0:96 offset1:112
	v_cvt_pk_bf16_f32 v2, v35, s0
	v_fmac_f32_e32 v21, v13, v47
	v_fmac_f32_e32 v10, v40, v49
	ds_write_b16 v1, v2 offset:1024
	v_cvt_pk_bf16_f32 v2, v40, s0
	v_fmac_f32_e32 v21, v4, v48
	v_fmac_f32_e32 v10, v41, v50
	ds_write_b16 v1, v2 offset:1152
	ds_write2_b32 v26, v4, v5 offset0:128 offset1:144
	v_cvt_pk_bf16_f32 v2, v41, s0
	v_fmac_f32_e32 v21, v5, v49
	v_fmac_f32_e32 v10, v59, v51
	ds_write_b16 v1, v2 offset:1280
	v_cvt_pk_bf16_f32 v2, v59, s0
	v_fmac_f32_e32 v21, v16, v50
	s_waitcnt lgkmcnt(14)
	v_fmac_f32_e32 v10, v68, v60
	ds_write_b16 v1, v2 offset:1408
	ds_write2_b32 v26, v16, v17 offset0:160 offset1:176
	v_cvt_pk_bf16_f32 v2, v68, s0
	v_fmac_f32_e32 v21, v17, v51
	v_fmac_f32_e32 v10, v65, v61
	ds_write_b16 v1, v2 offset:1536
	v_cvt_pk_bf16_f32 v2, v65, s0
	v_fmac_f32_e32 v21, v24, v60
	v_fmac_f32_e32 v10, v43, v62
	ds_write_b16 v1, v2 offset:1664
	ds_write2_b32 v26, v24, v25 offset0:192 offset1:208
	v_cvt_pk_bf16_f32 v2, v43, s0
	v_fmac_f32_e32 v21, v25, v61
	ds_write_b16 v1, v2 offset:1792
	v_cvt_pk_bf16_f32 v2, v10, s0
	v_fmac_f32_e32 v21, v20, v62
	ds_write_b16 v1, v2 offset:1920
	ds_write2_b32 v26, v20, v21 offset0:224 offset1:240
	s_waitcnt lgkmcnt(0)
	v_mov_b32_e32 v250, v6
	v_mov_b32_e32 v251, v7
	v_lshl_add_u64 v[6:7], v[6:7], 0, s[34:35]
	s_mov_b32 s100, 1
	s_waitcnt lgkmcnt(0)
	s_cbranch_scc0 .LBB0_890

; #define GAS __attribute__((address_space(1)))
; #define LAS __attribute__((address_space(3)))
; DI unsigned cvtpk(float lo, float hi) { typedef float f2 __attribute__((ext_vector_type(2))); typedef __bf16 b2 __attribute__((ext_vector_type(2))); f2 v = {lo, hi}; b2 b = __builtin_convertvector(v, b2); return __builtin_bit_cast(unsigned, b); }
; DI unsigned cvtpk(float lo, float hi) { typedef float f2 __attribute__((ext_vector_type(2))); typedef __bf16 b2 __attribute__((ext_vector_type(2))); f2 v = {lo, hi}; b2 b = __builtin_convertvector(v, b2); return __builtin_bit_cast(unsigned, b); }
; DI void chunk_prep(const bf16* PROJ, const float* mu, const bf16* LO, const float* pw0, const float* pa0, const float* pkk, const float* pka, const float* prk, float* SCAL, unsigned char* OPS, float* G15, LAS unsigned char* lds, int gw, int NGW, int wave, int lane) {
;     ...
;         unsigned char* ob = OPS + (size_t)task * OPS_TASK + lane * 16;
; #pragma unroll
;         for (int kb = 0; kb < 2; ++kb) { const int fo = (x * 64 + 32 * kb + 4 * q) * 2;
;             const v2u w0 = *(const LAS v2u*)(base + L_AT + fo), w1 = *(const LAS v2u*)(base + L_AT + fo + 32), r0 = *(const LAS v2u*)(base + L_RT + fo), r1 = *(const LAS v2u*)(base + L_RT + fo + 32);
;             *(GAS v4u*)(ob + kb * 1024) = (v4u){w0.x, w0.y, w1.x, w1.y}; *(GAS v4u*)(ob + (3 + kb) * 1024) = (v4u){r0.x, r0.y, r1.x, r1.y}; }
;         { const int go = (x * 16 + 4 * q) * 4; const f4 m2 = *(const LAS f4*)(base + L_AK + go), rb = *(const LAS f4*)(base + L_RB + go), rk = *(const LAS f4*)(base + L_RK + go);
;           *(GAS v4u*)(ob + 2 * 1024) = (v4u){0u, 0u, cvtpk(m2.x, m2.y), cvtpk(m2.z, m2.w)};
;           *(GAS v4u*)(ob + 5 * 1024) = (v4u){cvtpk(rb.x, rb.y), cvtpk(rb.z, rb.w), cvtpk(rk.x, rk.y), cvtpk(rk.z, rk.w)}; }
; #pragma unroll
;         for (int dt = 0; dt < 4; ++dt) { const int fo = ((16 * dt + x) * 16 + 4 * q) * 2; const v2u h = *(const LAS v2u*)(base + L_BH + fo), kk = *(const LAS v2u*)(base + L_KH + fo);
;             *(GAS v4u*)(ob + (6 + dt) * 1024) = (v4u){h.x, h.y, kk.x, kk.y}; }
.LBB0_890:
	s_cmp_eq_u32 s100, 0
	s_cbranch_scc1 .Lmy_cps_skip_exit
	s_mov_b32 s98, 0x87101000
	s_mov_b32 s99, 0
	v_lshl_add_u64 v[240:241], s[44:45], 0, v[250:251]
	v_add_u32_e32 v244, 0x800, v57
	ds_read2_b64 v[200:203], v57 offset1:4
	ds_read2_b64 v[204:207], v244 offset1:4
	ds_read2_b64 v[208:211], v57 offset0:8 offset1:12
	ds_read2_b64 v[212:215], v244 offset0:8 offset1:12
	ds_read_b128 v[216:219], v55 offset:13312
	ds_read_b128 v[220:223], v55 offset:14336
	ds_read_b128 v[224:227], v55 offset:15360
	ds_read2st64_b64 v[228:231], v58 offset0:16 offset1:20
	ds_read2st64_b64 v[232:235], v58 offset0:17 offset1:21
	ds_read2st64_b64 v[236:239], v58 offset0:18 offset1:22
	ds_read2st64_b64 v[246:249], v58 offset0:19 offset1:23
	v_lshl_add_u64 v[240:241], v[240:241], 0, s[98:99]
	s_movk_i32 s98, 0x1000
	v_mov_b32_e32 v192, 0
	v_mov_b32_e32 v193, 0
	v_lshl_add_u64 v[242:243], v[240:241], 0, s[98:99]
	s_waitcnt lgkmcnt(0)
	v_cvt_pk_bf16_f32 v194, v216, v217
	v_cvt_pk_bf16_f32 v195, v218, v219
	v_cvt_pk_bf16_f32 v196, v220, v221
	v_cvt_pk_bf16_f32 v197, v222, v223
	v_cvt_pk_bf16_f32 v198, v224, v225
	v_cvt_pk_bf16_f32 v199, v226, v227
	global_store_dwordx4 v[240:241], v[200:203], off offset:-4096
	global_store_dwordx4 v[240:241], v[208:211], off offset:-3072
	global_store_dwordx4 v[240:241], v[192:195], off offset:-2048
	global_store_dwordx4 v[240:241], v[204:207], off offset:-1024
	global_store_dwordx4 v[240:241], v[212:215], off
	global_store_dwordx4 v[240:241], v[196:199], off offset:1024
	global_store_dwordx4 v[240:241], v[228:231], off offset:2048
	global_store_dwordx4 v[240:241], v[232:235], off offset:3072
	global_store_dwordx4 v[242:243], v[236:239], off
	global_store_dwordx4 v[242:243], v[246:249], off offset:1024

; __global__ void __launch_bounds__(NWAVES * 64, 2) mk_fwd(Args args) {
	.amdhsa_kernel _Z6mk_fwd4Args
		.amdhsa_group_segment_fixed_size 0
		.amdhsa_private_segment_fixed_size 0
		.amdhsa_kernarg_size 576
		.amdhsa_user_sgpr_count 2
		.amdhsa_user_sgpr_dispatch_ptr 0
		.amdhsa_user_sgpr_queue_ptr 0
		.amdhsa_user_sgpr_kernarg_segment_ptr 1
		.amdhsa_user_sgpr_dispatch_id 0
		.amdhsa_user_sgpr_kernarg_preload_length 0
		.amdhsa_user_sgpr_kernarg_preload_offset 0
		.amdhsa_user_sgpr_private_segment_size 0
		.amdhsa_uses_dynamic_stack 0
		.amdhsa_enable_private_segment 0
		.amdhsa_system_sgpr_workgroup_id_x 1
		.amdhsa_system_sgpr_workgroup_id_y 0
		.amdhsa_system_sgpr_workgroup_id_z 0
		.amdhsa_system_sgpr_workgroup_info 0
		.amdhsa_system_vgpr_workitem_id 0
		.amdhsa_next_free_vgpr 255
		.amdhsa_next_free_sgpr 102
		.amdhsa_accum_offset 256
		.amdhsa_reserve_vcc 1
		.amdhsa_float_round_mode_32 0
		.amdhsa_float_round_mode_16_64 0
		.amdhsa_float_denorm_mode_32 3
		.amdhsa_float_denorm_mode_16_64 3
		.amdhsa_dx10_clamp 1
		.amdhsa_ieee_mode 1
		.amdhsa_fp16_overflow 0
		.amdhsa_tg_split 0
		.amdhsa_exception_fp_ieee_invalid_op 0
		.amdhsa_exception_fp_denorm_src 0
		.amdhsa_exception_fp_ieee_div_zero 0
		.amdhsa_exception_fp_ieee_overflow 0
		.amdhsa_exception_fp_ieee_underflow 0
		.amdhsa_exception_fp_ieee_inexact 0
		.amdhsa_exception_int_div_zero 0
	.end_amdhsa_kernel

; __global__ void __launch_bounds__(NWAVES * 64, 2) mk_fwd(Args args) {
amdhsa.kernels:
  - .agpr_count:     0
    .args:
      - .offset:         0
        .size:           320
        .value_kind:     by_value
      - .offset:         320
        .size:           4
        .value_kind:     hidden_block_count_x
      - .offset:         324
        .size:           4
        .value_kind:     hidden_block_count_y
      - .offset:         328
        .size:           4
        .value_kind:     hidden_block_count_z
      - .offset:         332
        .size:           2
        .value_kind:     hidden_group_size_x
      - .offset:         334
        .size:           2
        .value_kind:     hidden_group_size_y
      - .offset:         336
        .size:           2
        .value_kind:     hidden_group_size_z
      - .offset:         338
        .size:           2
        .value_kind:     hidden_remainder_x
      - .offset:         340
        .size:           2
        .value_kind:     hidden_remainder_y
      - .offset:         342
        .size:           2
        .value_kind:     hidden_remainder_z
      - .offset:         360
        .size:           8
        .value_kind:     hidden_global_offset_x
      - .offset:         368
        .size:           8
        .value_kind:     hidden_global_offset_y
      - .offset:         376
        .size:           8
        .value_kind:     hidden_global_offset_z
      - .offset:         384
        .size:           2
        .value_kind:     hidden_grid_dims
      - .offset:         440
        .size:           4
        .value_kind:     hidden_dynamic_lds_size
    .group_segment_fixed_size: 0
    .kernarg_segment_align: 8
    .kernarg_segment_size: 576
    .language:       OpenCL C
    .language_version:
      - 2
      - 0
    .max_flat_workgroup_size: 512
    .name:           _Z6mk_fwd4Args
    .private_segment_fixed_size: 0
    .sgpr_count:     108
    .sgpr_spill_count: 62
    .symbol:         _Z6mk_fwd4Args.kd
    .uniform_work_group_size: 1
    .uses_dynamic_stack: false
    .vgpr_count:     255
    .vgpr_spill_count: 0
    .wavefront_size: 64
